# in-proj epilogue: straight-line lean path for q/k/v tiles (no per-store branch ladder, stepped addresses)
# baseline (speedup 1.0000x reference)
;   __device__ __forceinline__ void operator()(const f32x4 (&acc)[2][2][4][2], const pg8::Unit& u, int wr, int wc, int fr, int fq) const {
;     ...
;       } else {
;         u16* qkv = (u16*)(ws + O_QKV); u16* sg = (u16*)(ws + O_SG + (size_t)(slice & 1) * SG_BYTES);
;         const bool isg = (u.pn >= 30);
;         float rsv[2][4];
; #pragma unroll
;         for (int ai = 0; ai < 2; ++ai)
; #pragma unroll
;           for (int m = 0; m < 4; ++m) rsv[ai][m] = rstd1[row0 + ai * 128 + m * 16];
;         __builtin_amdgcn_sched_barrier(0);
; #pragma unroll
;         for (int ai = 0; ai < 2; ++ai)
; #pragma unroll
;           for (int m = 0; m < 4; ++m) {
;             const int row = row0 + ai * 128 + m * 16; const float rs = rsv[ai][m];
.LBB0_155:
	s_andn2_b64 vcc, exec, s[10:11]
	s_cbranch_vccnz .LBB0_284
	v_ashrrev_i32_e32 v177, 31, v176
	v_lshl_add_u64 v[130:131], v[176:177], 2, s[82:83]
	flat_load_dword v148, v[130:131]
	flat_load_dword v146, v[130:131] offset:64
	flat_load_dword v144, v[130:131] offset:128
	flat_load_dword v142, v[130:131] offset:192
	flat_load_dword v140, v[130:131] offset:512
	flat_load_dword v138, v[130:131] offset:576
	flat_load_dword v136, v[130:131] offset:640
	flat_load_dword v134, v[130:131] offset:704
	s_cmp_lt_i32 s72, 30
	s_cselect_b64 s[0:1], -1, 0
	s_cmp_gt_i32 s72, 29
	s_waitcnt vmcnt(0) lgkmcnt(0)
	s_cmp_lt_i32 s72, 30
	s_cbranch_scc1 .Lqkv_lean
	s_cmp_gt_i32 s72, 29
	v_pk_mul_f32 v[132:133], v[128:129], v[148:149] op_sel_hi:[1,0]
	v_pk_mul_f32 v[130:131], v[126:127], v[148:149] op_sel_hi:[1,0]
	v_pk_mul_f32 v[150:151], v[124:125], v[148:149] op_sel_hi:[1,0]
	v_pk_mul_f32 v[152:153], v[122:123], v[148:149] op_sel_hi:[1,0]
	s_mov_b64 s[10:11], -1
	s_cbranch_scc1 .LBB0_158
	s_mov_b64 s[10:11], 0

; __device__ __forceinline__ unsigned pk2(float lo, float hi) { const f32x2_t f = {lo, hi}; const bf16x2_t b = __builtin_convertvector(f, bf16x2_t); return __builtin_bit_cast(unsigned, b); }
;   __device__ __forceinline__ void operator()(const f32x4 (&acc)[2][2][4][2], const pg8::Unit& u, int wr, int wc, int fr, int fq) const {
;     ...
; #pragma unroll
;         for (int ai = 0; ai < 2; ++ai)
; #pragma unroll
;           for (int m = 0; m < 4; ++m) {
;             const int row = row0 + ai * 128 + m * 16; const float rs = rsv[ai][m];
; #pragma unroll
;             for (int bj = 0; bj < 2; ++bj) {
;               const int c = col0 + bj * 128;
;               f32x4 a = acc[ai][bj][m][0] * rs, b = acc[ai][bj][m][1] * rs;
;               if (isg) {
; #pragma unroll
;                 for (int e = 0; e < 4; ++e) { a[e] = __builtin_amdgcn_rcpf(1.0f + __expf(-a[e])); b[e] = __builtin_amdgcn_rcpf(1.0f + __expf(-b[e])); }
;               }
;               u32x4 o; o.x = pk2(a[0], a[1]); o.y = pk2(a[2], a[3]); o.z = pk2(b[0], b[1]); o.w = pk2(b[2], b[3]);
;               if (isg) *(u32x4*)(sg + (size_t)row * 2048 + (c - 7680)) = o; else *(u32x4*)(qkv + (size_t)row * 4608 + c) = o;
.LBB0_282:
	s_andn2_b64 vcc, exec, s[0:1]
	s_cbranch_vccnz .LBB0_284
	v_add_co_u32_e32 v134, vcc, 0x2584e000, v138
	s_nop 1
	v_addc_co_u32_e32 v135, vcc, 0, v139, vcc
	flat_store_dwordx4 v[134:135], v[130:133] offset:1280
	s_branch .LBB0_284
.Lqkv_lean:
	v_mov_b64_e32 v[154:155], s[30:31]
	s_movk_i32 s10, 0x2400
	v_mad_i64_i32 v[154:155], vcc, v176, s10, v[154:155]
	s_mov_b32 s12, 0x24000
	s_mov_b32 s13, 0
	s_mov_b32 s0, 0xb4000
	s_mov_b32 s1, 0
	v_lshl_add_u64 v[194:195], v[174:175], 1, v[154:155]
	v_pk_mul_f32 v[150:151], v[126:127], v[148:149] op_sel_hi:[1,0]
	v_pk_mul_f32 v[152:153], v[128:129], v[148:149] op_sel_hi:[1,0]
	v_pk_mul_f32 v[154:155], v[122:123], v[148:149] op_sel_hi:[1,0]
	v_pk_mul_f32 v[156:157], v[124:125], v[148:149] op_sel_hi:[1,0]
	v_cvt_pk_bf16_f32 v158, v150, v151
	v_cvt_pk_bf16_f32 v159, v152, v153
	v_cvt_pk_bf16_f32 v160, v154, v155
	v_cvt_pk_bf16_f32 v161, v156, v157
	global_store_dwordx4 v[194:195], v[158:161], off
	v_pk_mul_f32 v[178:179], v[60:61], v[148:149] op_sel_hi:[1,0]
	v_pk_mul_f32 v[180:181], v[62:63], v[148:149] op_sel_hi:[1,0]
	v_pk_mul_f32 v[182:183], v[56:57], v[148:149] op_sel_hi:[1,0]
	v_pk_mul_f32 v[184:185], v[58:59], v[148:149] op_sel_hi:[1,0]
	v_cvt_pk_bf16_f32 v190, v178, v179
	v_cvt_pk_bf16_f32 v191, v180, v181
	v_cvt_pk_bf16_f32 v192, v182, v183
	v_cvt_pk_bf16_f32 v193, v184, v185
	global_store_dwordx4 v[194:195], v[190:193], off offset:256
	v_lshl_add_u64 v[196:197], s[12:13], 0, v[194:195]
	v_pk_mul_f32 v[150:151], v[118:119], v[146:147] op_sel_hi:[1,0]
	v_pk_mul_f32 v[152:153], v[120:121], v[146:147] op_sel_hi:[1,0]
	v_pk_mul_f32 v[154:155], v[114:115], v[146:147] op_sel_hi:[1,0]
	v_pk_mul_f32 v[156:157], v[116:117], v[146:147] op_sel_hi:[1,0]
	v_cvt_pk_bf16_f32 v158, v150, v151
	v_cvt_pk_bf16_f32 v159, v152, v153
	v_cvt_pk_bf16_f32 v160, v154, v155
	v_cvt_pk_bf16_f32 v161, v156, v157
	global_store_dwordx4 v[196:197], v[158:161], off
	v_pk_mul_f32 v[178:179], v[52:53], v[146:147] op_sel_hi:[1,0]
	v_pk_mul_f32 v[180:181], v[54:55], v[146:147] op_sel_hi:[1,0]
	v_pk_mul_f32 v[182:183], v[48:49], v[146:147] op_sel_hi:[1,0]
	v_pk_mul_f32 v[184:185], v[50:51], v[146:147] op_sel_hi:[1,0]
	v_cvt_pk_bf16_f32 v190, v178, v179
	v_cvt_pk_bf16_f32 v191, v180, v181
	v_cvt_pk_bf16_f32 v192, v182, v183
	v_cvt_pk_bf16_f32 v193, v184, v185
	global_store_dwordx4 v[196:197], v[190:193], off offset:256
	v_lshl_add_u64 v[194:195], s[12:13], 0, v[196:197]
	v_pk_mul_f32 v[150:151], v[110:111], v[144:145] op_sel_hi:[1,0]
	v_pk_mul_f32 v[152:153], v[112:113], v[144:145] op_sel_hi:[1,0]
	v_pk_mul_f32 v[154:155], v[106:107], v[144:145] op_sel_hi:[1,0]
	v_pk_mul_f32 v[156:157], v[108:109], v[144:145] op_sel_hi:[1,0]
	v_cvt_pk_bf16_f32 v158, v150, v151
	v_cvt_pk_bf16_f32 v159, v152, v153
	v_cvt_pk_bf16_f32 v160, v154, v155
	v_cvt_pk_bf16_f32 v161, v156, v157
	global_store_dwordx4 v[194:195], v[158:161], off
	v_pk_mul_f32 v[178:179], v[44:45], v[144:145] op_sel_hi:[1,0]
	v_pk_mul_f32 v[180:181], v[46:47], v[144:145] op_sel_hi:[1,0]
	v_pk_mul_f32 v[182:183], v[40:41], v[144:145] op_sel_hi:[1,0]
	v_pk_mul_f32 v[184:185], v[42:43], v[144:145] op_sel_hi:[1,0]
	v_cvt_pk_bf16_f32 v190, v178, v179
	v_cvt_pk_bf16_f32 v191, v180, v181
	v_cvt_pk_bf16_f32 v192, v182, v183
	v_cvt_pk_bf16_f32 v193, v184, v185
	global_store_dwordx4 v[194:195], v[190:193], off offset:256
	v_lshl_add_u64 v[196:197], s[12:13], 0, v[194:195]
	v_pk_mul_f32 v[150:151], v[102:103], v[142:143] op_sel_hi:[1,0]
	v_pk_mul_f32 v[152:153], v[104:105], v[142:143] op_sel_hi:[1,0]
	v_pk_mul_f32 v[154:155], v[98:99], v[142:143] op_sel_hi:[1,0]
	v_pk_mul_f32 v[156:157], v[100:101], v[142:143] op_sel_hi:[1,0]
	v_cvt_pk_bf16_f32 v158, v150, v151
	v_cvt_pk_bf16_f32 v159, v152, v153
	v_cvt_pk_bf16_f32 v160, v154, v155
	v_cvt_pk_bf16_f32 v161, v156, v157
	global_store_dwordx4 v[196:197], v[158:161], off
	v_pk_mul_f32 v[178:179], v[36:37], v[142:143] op_sel_hi:[1,0]
	v_pk_mul_f32 v[180:181], v[38:39], v[142:143] op_sel_hi:[1,0]
	v_pk_mul_f32 v[182:183], v[32:33], v[142:143] op_sel_hi:[1,0]
; __device__ __forceinline__ unsigned pk2(float lo, float hi) { const f32x2_t f = {lo, hi}; const bf16x2_t b = __builtin_convertvector(f, bf16x2_t); return __builtin_bit_cast(unsigned, b); }
;   __device__ __forceinline__ void operator()(const f32x4 (&acc)[2][2][4][2], const pg8::Unit& u, int wr, int wc, int fr, int fq) const {
;     ...
; #pragma unroll
;         for (int ai = 0; ai < 2; ++ai)
; #pragma unroll
;           for (int m = 0; m < 4; ++m) {
;             const int row = row0 + ai * 128 + m * 16; const float rs = rsv[ai][m];
; #pragma unroll
;             for (int bj = 0; bj < 2; ++bj) {
;               const int c = col0 + bj * 128;
;               f32x4 a = acc[ai][bj][m][0] * rs, b = acc[ai][bj][m][1] * rs;
;               if (isg) {
; #pragma unroll
;                 for (int e = 0; e < 4; ++e) { a[e] = __builtin_amdgcn_rcpf(1.0f + __expf(-a[e])); b[e] = __builtin_amdgcn_rcpf(1.0f + __expf(-b[e])); }
;               }
;               u32x4 o; o.x = pk2(a[0], a[1]); o.y = pk2(a[2], a[3]); o.z = pk2(b[0], b[1]); o.w = pk2(b[2], b[3]);
;               if (isg) *(u32x4*)(sg + (size_t)row * 2048 + (c - 7680)) = o; else *(u32x4*)(qkv + (size_t)row * 4608 + c) = o;
	v_pk_mul_f32 v[184:185], v[34:35], v[142:143] op_sel_hi:[1,0]
	v_cvt_pk_bf16_f32 v190, v178, v179
	v_cvt_pk_bf16_f32 v191, v180, v181
	v_cvt_pk_bf16_f32 v192, v182, v183
	v_cvt_pk_bf16_f32 v193, v184, v185
	global_store_dwordx4 v[196:197], v[190:193], off offset:256
	v_lshl_add_u64 v[194:195], s[0:1], 0, v[196:197]
	v_pk_mul_f32 v[150:151], v[94:95], v[140:141] op_sel_hi:[1,0]
	v_pk_mul_f32 v[152:153], v[96:97], v[140:141] op_sel_hi:[1,0]
	v_pk_mul_f32 v[154:155], v[90:91], v[140:141] op_sel_hi:[1,0]
	v_pk_mul_f32 v[156:157], v[92:93], v[140:141] op_sel_hi:[1,0]
	v_cvt_pk_bf16_f32 v158, v150, v151
	v_cvt_pk_bf16_f32 v159, v152, v153
	v_cvt_pk_bf16_f32 v160, v154, v155
	v_cvt_pk_bf16_f32 v161, v156, v157
	global_store_dwordx4 v[194:195], v[158:161], off
	v_pk_mul_f32 v[178:179], v[28:29], v[140:141] op_sel_hi:[1,0]
	v_pk_mul_f32 v[180:181], v[30:31], v[140:141] op_sel_hi:[1,0]
	v_pk_mul_f32 v[182:183], v[24:25], v[140:141] op_sel_hi:[1,0]
	v_pk_mul_f32 v[184:185], v[26:27], v[140:141] op_sel_hi:[1,0]
	v_cvt_pk_bf16_f32 v190, v178, v179
	v_cvt_pk_bf16_f32 v191, v180, v181
	v_cvt_pk_bf16_f32 v192, v182, v183
	v_cvt_pk_bf16_f32 v193, v184, v185
	global_store_dwordx4 v[194:195], v[190:193], off offset:256
	v_lshl_add_u64 v[196:197], s[12:13], 0, v[194:195]
	v_pk_mul_f32 v[150:151], v[86:87], v[138:139] op_sel_hi:[1,0]
	v_pk_mul_f32 v[152:153], v[88:89], v[138:139] op_sel_hi:[1,0]
	v_pk_mul_f32 v[154:155], v[82:83], v[138:139] op_sel_hi:[1,0]
	v_pk_mul_f32 v[156:157], v[84:85], v[138:139] op_sel_hi:[1,0]
	v_cvt_pk_bf16_f32 v158, v150, v151
	v_cvt_pk_bf16_f32 v159, v152, v153
	v_cvt_pk_bf16_f32 v160, v154, v155
	v_cvt_pk_bf16_f32 v161, v156, v157
	global_store_dwordx4 v[196:197], v[158:161], off
	v_pk_mul_f32 v[178:179], v[20:21], v[138:139] op_sel_hi:[1,0]
	v_pk_mul_f32 v[180:181], v[22:23], v[138:139] op_sel_hi:[1,0]
	v_pk_mul_f32 v[182:183], v[16:17], v[138:139] op_sel_hi:[1,0]
	v_pk_mul_f32 v[184:185], v[18:19], v[138:139] op_sel_hi:[1,0]
	v_cvt_pk_bf16_f32 v190, v178, v179
	v_cvt_pk_bf16_f32 v191, v180, v181
	v_cvt_pk_bf16_f32 v192, v182, v183
	v_cvt_pk_bf16_f32 v193, v184, v185
	global_store_dwordx4 v[196:197], v[190:193], off offset:256
	v_lshl_add_u64 v[194:195], s[12:13], 0, v[196:197]
	v_pk_mul_f32 v[150:151], v[76:77], v[136:137] op_sel_hi:[1,0]
	v_pk_mul_f32 v[152:153], v[78:79], v[136:137] op_sel_hi:[1,0]
	v_pk_mul_f32 v[154:155], v[72:73], v[136:137] op_sel_hi:[1,0]
	v_pk_mul_f32 v[156:157], v[74:75], v[136:137] op_sel_hi:[1,0]
	v_cvt_pk_bf16_f32 v158, v150, v151
	v_cvt_pk_bf16_f32 v159, v152, v153
	v_cvt_pk_bf16_f32 v160, v154, v155
	v_cvt_pk_bf16_f32 v161, v156, v157
	global_store_dwordx4 v[194:195], v[158:161], off
	v_pk_mul_f32 v[178:179], v[12:13], v[136:137] op_sel_hi:[1,0]
	v_pk_mul_f32 v[180:181], v[14:15], v[136:137] op_sel_hi:[1,0]
	v_pk_mul_f32 v[182:183], v[8:9], v[136:137] op_sel_hi:[1,0]
	v_pk_mul_f32 v[184:185], v[10:11], v[136:137] op_sel_hi:[1,0]
	v_cvt_pk_bf16_f32 v190, v178, v179
	v_cvt_pk_bf16_f32 v191, v180, v181
	v_cvt_pk_bf16_f32 v192, v182, v183
	v_cvt_pk_bf16_f32 v193, v184, v185
	global_store_dwordx4 v[194:195], v[190:193], off offset:256
	v_lshl_add_u64 v[196:197], s[12:13], 0, v[194:195]
	v_pk_mul_f32 v[150:151], v[68:69], v[134:135] op_sel_hi:[1,0]
	v_pk_mul_f32 v[152:153], v[70:71], v[134:135] op_sel_hi:[1,0]
	v_pk_mul_f32 v[154:155], v[64:65], v[134:135] op_sel_hi:[1,0]
	v_pk_mul_f32 v[156:157], v[66:67], v[134:135] op_sel_hi:[1,0]
	v_cvt_pk_bf16_f32 v158, v150, v151
	v_cvt_pk_bf16_f32 v159, v152, v153
	v_cvt_pk_bf16_f32 v160, v154, v155
	v_cvt_pk_bf16_f32 v161, v156, v157
	global_store_dwordx4 v[196:197], v[158:161], off
	v_pk_mul_f32 v[178:179], v[4:5], v[134:135] op_sel_hi:[1,0]
	v_pk_mul_f32 v[180:181], v[6:7], v[134:135] op_sel_hi:[1,0]
	v_pk_mul_f32 v[182:183], v[0:1], v[134:135] op_sel_hi:[1,0]
	v_pk_mul_f32 v[184:185], v[2:3], v[134:135] op_sel_hi:[1,0]
	v_cvt_pk_bf16_f32 v190, v178, v179
	v_cvt_pk_bf16_f32 v191, v180, v181
	v_cvt_pk_bf16_f32 v192, v182, v183
	v_cvt_pk_bf16_f32 v193, v184, v185
	global_store_dwordx4 v[196:197], v[190:193], off offset:256
	s_branch .LBB0_284
